# attn M phases: K-fragment LDS addresses from pre-summed per-unit bases (one fewer VALU per tile)
# baseline (speedup 1.0000x reference)
; __device__ __forceinline__ void softmaxT(f32x16& p0, f32x16& p1, float& mref, f32x16& negm, float& l_reg, float& alpha, bf16x8& pa0, bf16x8& pa1, bf16x8& pa2, bf16x8& pa3) {
;     ...
;   { float s0 = p0[0] + p1[0], s1 = p0[1] + p1[1], s2 = p0[2] + p1[2], s3 = p0[3] + p1[3];
; #pragma unroll
;     for (int r = 4; r < 16; r += 4) { s0 += p0[r] + p1[r]; s1 += p0[r + 1] + p1[r + 1]; s2 += p0[r + 2] + p1[r + 2]; s3 += p0[r + 3] + p1[r + 3]; }
;     l_reg += (s0 + s1) + (s2 + s3); }
.LBB0_523:
	v_add_f32_e32 v66, v159, v66
	v_add_f32_e32 v70, v179, v70
	v_add_f32_e32 v67, v160, v67
	v_add_f32_e32 v66, v70, v66
	v_add_f32_e32 v70, v180, v71
	v_add_f32_e32 v68, v161, v68
	v_add_f32_e32 v67, v70, v67
	v_add_f32_e32 v70, v181, v72
	v_add_f32_e32 v69, v178, v69
	v_add_f32_e32 v68, v70, v68
	v_add_f32_e32 v70, v182, v73
	v_add_f32_e32 v69, v70, v69
	v_add_f32_e32 v70, v183, v74
	v_add_f32_e32 v66, v70, v66
	v_add_f32_e32 v70, v184, v75
	v_add_f32_e32 v67, v70, v67
	v_add_f32_e32 v70, v185, v76
	v_add_f32_e32 v68, v70, v68
	v_add_f32_e32 v70, v186, v77
	v_add_f32_e32 v69, v70, v69
	v_add_f32_e32 v70, v187, v78
	v_add_f32_e32 v66, v70, v66
	v_add_f32_e32 v70, v188, v79
	v_add_f32_e32 v67, v70, v67
	v_add_f32_e32 v70, v189, v80
	v_add_f32_e32 v68, v70, v68
	v_add_f32_e32 v70, v190, v81
	v_add_f32_e32 v69, v70, v69
	v_add_f32_e32 v66, v67, v66
	v_add_f32_e32 v67, v69, v68
	v_add_f32_e32 v66, v67, v66
	v_add_f32_e32 v157, v157, v66
	v_add_u32_e32 v66, s64, v131
	v_readlane_b32 s0, v255, 14
	s_waitcnt vmcnt(3)
	s_waitcnt vmcnt(3)
	ds_write_b128 v66, v[126:129]
	v_add_u32_e32 v66, s64, v133
	s_or_b32 s0, s4, s0
	ds_write_b128 v66, v[122:125]
	v_add_u32_e32 v66, s64, v145
	s_ashr_i32 s1, s0, 31
	ds_write_b128 v66, v[118:121] offset:49152
	v_lshl_add_u64 v[66:67], v[134:135], 0, s[0:1]
	v_lshlrev_b64 v[66:67], 11, v[66:67]
	v_lshl_add_u64 v[66:67], v[138:139], 0, v[66:67]
	global_load_dwordx4 v[118:121], v[66:67], off
	v_lshl_add_u64 v[66:67], v[136:137], 0, s[0:1]
	v_lshlrev_b64 v[66:67], 11, v[66:67]
	v_lshl_add_u64 v[66:67], v[138:139], 0, v[66:67]
	global_load_dwordx4 v[122:125], v[66:67], off
	v_mov_b32_e32 v67, s1
	v_or_b32_e32 v66, s0, v144
	v_lshlrev_b64 v[66:67], 6, v[66:67]
	v_lshl_add_u64 v[66:67], v[140:141], 0, v[66:67]
	global_load_dwordx4 v[126:129], v[66:67], off
	v_lshlrev_b64 v[216:217], 11, v[134:135]
	v_lshlrev_b64 v[218:219], 11, v[136:137]
	v_lshlrev_b32_e32 v220, 6, v144
	v_mov_b32_e32 v221, 0
	v_lshl_add_u64 v[216:217], v[138:139], 0, v[216:217]
	v_lshl_add_u64 v[218:219], v[138:139], 0, v[218:219]
	v_lshl_add_u64 v[220:221], v[140:141], 0, v[220:221]
	v_add_u32_e32 v239, v146, v147
	v_add_u32_e32 v250, v146, v148
	v_add_u32_e32 v251, v146, v149
	v_add_u32_e32 v252, v146, v150
	v_add_u32_e32 v253, v146, v151
	v_add_u32_e32 v175, v146, v152
	s_addk_i32 s4, 0xff80
	s_mov_b32 s5, 0x8000
	s_mov_b32 s10, 0
	s_movk_i32 s0, 0x4000
	s_mov_b32 s11, 2
	s_waitcnt lgkmcnt(0)
	s_barrier

; #define LAS __attribute__((address_space(3)))
; __device__ __forceinline__ void qkt(f32x16& p0, f32x16& p1, const LAS unsigned char* Ks, const bf16x8* qr, const f32x16& negm, int r32, int hi) {
;   bf16x8 kf[12];
; #pragma unroll
;   for (int d0 = 0; d0 < 6; ++d0) { const int cb = (d0 * 16 + hi * 8) * 2;
;     kf[2 * d0] = *(const LAS bf16x8*)(Ks + KSWZ(r32, cb)); kf[2 * d0 + 1] = *(const LAS bf16x8*)(Ks + KSWZ(32 + r32, cb)); }
;   SBAR();
;   p0 = __builtin_amdgcn_mfma_f32_32x32x16_bf16(kf[0], qr[0], negm, 0, 0, 0); p1 = __builtin_amdgcn_mfma_f32_32x32x16_bf16(kf[1], qr[0], negm, 0, 0, 0);
; #pragma unroll
;   for (int d0 = 1; d0 < 6; ++d0) { p0 = __builtin_amdgcn_mfma_f32_32x32x16_bf16(kf[2 * d0], qr[d0], p0, 0, 0, 0); p1 = __builtin_amdgcn_mfma_f32_32x32x16_bf16(kf[2 * d0 + 1], qr[d0], p1, 0, 0, 0); }
; }
; __device__ __forceinline__ int v_st(int k, int c) { const int kk = (k & ~0xC) | ((k & 4) << 1) | ((k & 8) >> 1); return ((kk >> 3) * 4 + (c >> 5)) * 512 + ((kk & 7) * 32 + (c & 31)) * 2; }
; __device__ __forceinline__ int v_rd_base(int lane) { return ((lane & 3) << 3) | (((lane >> 2) & 3) << 6) | (((lane >> 4) & 1) << 5) | (((lane >> 5) & 1) << 8); }
; template <int OFF> __device__ __forceinline__ s16x4 tr_read(int vb) {
;   s16x4 r; asm volatile("ds_read_b64_tr_b16 %0, %1 offset:%2" : "=&v"(r) : "v"(vb), "i"(OFF) : "memory"); return r;
; }
; __device__ __forceinline__ void pv_d0(f32x16* o, int vb, bf16x8 pa0, bf16x8 pa1, bf16x8 pa2, bf16x8 pa3) {
;   const s16x4 a0 = tr_read<v_rd_off(0, 0, 0)>(vb), b0 = tr_read<v_rd_off(0, 0, 1)>(vb), a1 = tr_read<v_rd_off(0, 1, 0)>(vb), b1 = tr_read<v_rd_off(0, 1, 1)>(vb);
;   const s16x4 a2 = tr_read<v_rd_off(0, 2, 0)>(vb), b2 = tr_read<v_rd_off(0, 2, 1)>(vb), a3 = tr_read<v_rd_off(0, 3, 0)>(vb), b3 = tr_read<v_rd_off(0, 3, 1)>(vb);
;   const s16x4 c0 = tr_read<v_rd_off(1, 0, 0)>(vb), d0 = tr_read<v_rd_off(1, 0, 1)>(vb), c1 = tr_read<v_rd_off(1, 1, 0)>(vb), d1 = tr_read<v_rd_off(1, 1, 1)>(vb);
;   const s16x4 c2 = tr_read<v_rd_off(1, 2, 0)>(vb), d2 = tr_read<v_rd_off(1, 2, 1)>(vb), c3 = tr_read<v_rd_off(1, 3, 0)>(vb), d3 = tr_read<v_rd_off(1, 3, 1)>(vb);
;   asm volatile("s_waitcnt lgkmcnt(0)" ::: "memory"); SBAR();
;     ...
;   o[0] = __builtin_amdgcn_mfma_f32_32x32x16_bf16(pa0, PK(a0, b0), o[0], 0, 0, 0); o[1] = __builtin_amdgcn_mfma_f32_32x32x16_bf16(pa0, PK(c0, d0), o[1], 0, 0, 0);
.Lmy_attn_m1:
	ds_read_b64_tr_b16 v[70:71], v174 offset:0x1000
	ds_read_b64_tr_b16 v[72:73], v174 offset:0x1800
	ds_read_b64_tr_b16 v[162:163], v174 offset:0x1200
	ds_read_b64_tr_b16 v[164:165], v174 offset:0x1a00
	ds_read_b64_tr_b16 v[74:75], v174 offset:0x2000
	ds_read_b64_tr_b16 v[76:77], v174 offset:0x2800
	ds_read_b64_tr_b16 v[166:167], v174 offset:0x2200
	ds_read_b64_tr_b16 v[168:169], v174 offset:0x2a00
	ds_read_b64_tr_b16 v[78:79], v174 offset:0x3000
	ds_read_b64_tr_b16 v[80:81], v174 offset:0x3800
	ds_read_b64_tr_b16 v[170:171], v174 offset:0x3200
	ds_read_b64_tr_b16 v[172:173], v174 offset:0x3a00
	s_waitcnt lgkmcnt(14)
	v_mfma_f32_32x32x16_bf16 v[34:49], v[62:65], v[66:69], v[34:49]
	s_waitcnt lgkmcnt(12)
	v_mfma_f32_32x32x16_bf16 v[18:33], v[62:65], v[158:161], v[18:33]
	s_waitcnt lgkmcnt(10)
	v_mfma_f32_32x32x16_bf16 v[34:49], v[50:53], v[70:73], v[34:49]
	s_waitcnt lgkmcnt(8)
	v_mfma_f32_32x32x16_bf16 v[18:33], v[50:53], v[162:165], v[18:33]
	s_waitcnt lgkmcnt(6)
	v_mfma_f32_32x32x16_bf16 v[34:49], v[54:57], v[74:77], v[34:49]
	s_waitcnt lgkmcnt(4)
	v_mfma_f32_32x32x16_bf16 v[18:33], v[54:57], v[166:169], v[18:33]
	v_add_u32_e32 v55, s5, v239
	ds_read_b128 v[50:53], v55 offset:49152
	ds_read_b128 v[158:161], v55 offset:57344
	v_add_u32_e32 v55, s5, v250
	ds_read_b128 v[162:165], v55 offset:49152
	ds_read_b128 v[166:169], v55 offset:57344
	v_add_u32_e32 v55, s5, v251
	s_waitcnt lgkmcnt(6)
	v_mfma_f32_32x32x16_bf16 v[34:49], v[58:61], v[78:81], v[34:49]
	s_waitcnt lgkmcnt(4)
	v_mfma_f32_32x32x16_bf16 v[18:33], v[58:61], v[170:173], v[18:33]
	ds_read_b128 v[170:173], v55 offset:49152
	ds_read_b128 v[178:181], v55 offset:57344
	v_add_u32_e32 v55, s5, v252
	ds_read_b128 v[182:185], v55 offset:49152
	ds_read_b128 v[186:189], v55 offset:57344
	v_add_u32_e32 v55, s5, v253
	v_add_u32_e32 v54, s5, v175
	ds_read_b128 v[190:193], v55 offset:49152
	ds_read_b128 v[194:197], v55 offset:57344
	ds_read_b128 v[198:201], v54 offset:49152
	ds_read_b128 v[202:205], v54 offset:57344
	s_waitcnt lgkmcnt(11)
	v_mfma_f32_32x32x16_bf16 v[66:81], v[50:53], v[82:85], v[2:17]
	s_waitcnt lgkmcnt(9)
	v_mfma_f32_32x32x16_bf16 v[66:81], v[162:165], v[86:89], v[66:81]
	s_waitcnt lgkmcnt(7)
	v_mfma_f32_32x32x16_bf16 v[66:81], v[170:173], v[90:93], v[66:81]
	s_waitcnt lgkmcnt(5)
	v_mfma_f32_32x32x16_bf16 v[66:81], v[182:185], v[94:97], v[66:81]
	s_waitcnt lgkmcnt(3)
	v_mfma_f32_32x32x16_bf16 v[66:81], v[190:193], v[98:101], v[66:81]
	s_waitcnt lgkmcnt(1)
	v_mfma_f32_32x32x16_bf16 v[66:81], v[198:201], v[102:105], v[66:81]
	s_waitcnt lgkmcnt(0)
	v_mfma_f32_32x32x16_bf16 v[50:65], v[158:161], v[82:85], v[2:17]
	v_mfma_f32_32x32x16_bf16 v[50:65], v[166:169], v[86:89], v[50:65]
	v_mfma_f32_32x32x16_bf16 v[50:65], v[178:181], v[90:93], v[50:65]
	v_mfma_f32_32x32x16_bf16 v[50:65], v[186:189], v[94:97], v[50:65]
	v_mfma_f32_32x32x16_bf16 v[50:65], v[194:197], v[98:101], v[50:65]
	v_mfma_f32_32x32x16_bf16 v[50:65], v[202:205], v[102:105], v[50:65]
	s_setprio 0
	v_max3_f32 v158, v66, v67, v68
	v_max3_f32 v159, v69, v70, v71
	v_max3_f32 v158, v158, v72, v73
	v_max3_f32 v159, v159, v74, v75
	v_max3_f32 v158, v158, v76, v77
	v_max3_f32 v159, v159, v78, v79
	v_max3_f32 v158, v158, v80, v81
	s_nop 3
	v_max3_f32 v159, v159, v50, v51
	v_max3_f32 v158, v158, v52, v53
	v_max3_f32 v159, v159, v54, v55
	v_max3_f32 v158, v158, v56, v57
	v_max3_f32 v159, v159, v58, v59
	v_max3_f32 v158, v158, v60, v61
	v_max3_f32 v159, v159, v62, v63
	v_max3_f32 v158, v158, v64, v65
	v_max_f32_e32 v159, v158, v159
	v_cmp_ge_f32_e32 vcc, s93, v159
	s_cmp_eq_u64 vcc, exec
	s_barrier
	s_cbranch_scc0 .LBB0_540

; #define LAS __attribute__((address_space(3)))
; __device__ __forceinline__ void qkt(f32x16& p0, f32x16& p1, const LAS unsigned char* Ks, const bf16x8* qr, const f32x16& negm, int r32, int hi) {
;   bf16x8 kf[12];
; #pragma unroll
;   for (int d0 = 0; d0 < 6; ++d0) { const int cb = (d0 * 16 + hi * 8) * 2;
;     kf[2 * d0] = *(const LAS bf16x8*)(Ks + KSWZ(r32, cb)); kf[2 * d0 + 1] = *(const LAS bf16x8*)(Ks + KSWZ(32 + r32, cb)); }
;   SBAR();
;   p0 = __builtin_amdgcn_mfma_f32_32x32x16_bf16(kf[0], qr[0], negm, 0, 0, 0); p1 = __builtin_amdgcn_mfma_f32_32x32x16_bf16(kf[1], qr[0], negm, 0, 0, 0);
; #pragma unroll
;   for (int d0 = 1; d0 < 6; ++d0) { p0 = __builtin_amdgcn_mfma_f32_32x32x16_bf16(kf[2 * d0], qr[d0], p0, 0, 0, 0); p1 = __builtin_amdgcn_mfma_f32_32x32x16_bf16(kf[2 * d0 + 1], qr[d0], p1, 0, 0, 0); }
; }
; __device__ __forceinline__ int v_st(int k, int c) { const int kk = (k & ~0xC) | ((k & 4) << 1) | ((k & 8) >> 1); return ((kk >> 3) * 4 + (c >> 5)) * 512 + ((kk & 7) * 32 + (c & 31)) * 2; }
; __device__ __forceinline__ int v_rd_base(int lane) { return ((lane & 3) << 3) | (((lane >> 2) & 3) << 6) | (((lane >> 4) & 1) << 5) | (((lane >> 5) & 1) << 8); }
; template <int OFF> __device__ __forceinline__ s16x4 tr_read(int vb) {
;   s16x4 r; asm volatile("ds_read_b64_tr_b16 %0, %1 offset:%2" : "=&v"(r) : "v"(vb), "i"(OFF) : "memory"); return r;
; }
; __device__ __forceinline__ void pv_d0(f32x16* o, int vb, bf16x8 pa0, bf16x8 pa1, bf16x8 pa2, bf16x8 pa3) {
;   const s16x4 a0 = tr_read<v_rd_off(0, 0, 0)>(vb), b0 = tr_read<v_rd_off(0, 0, 1)>(vb), a1 = tr_read<v_rd_off(0, 1, 0)>(vb), b1 = tr_read<v_rd_off(0, 1, 1)>(vb);
;   const s16x4 a2 = tr_read<v_rd_off(0, 2, 0)>(vb), b2 = tr_read<v_rd_off(0, 2, 1)>(vb), a3 = tr_read<v_rd_off(0, 3, 0)>(vb), b3 = tr_read<v_rd_off(0, 3, 1)>(vb);
;   const s16x4 c0 = tr_read<v_rd_off(1, 0, 0)>(vb), d0 = tr_read<v_rd_off(1, 0, 1)>(vb), c1 = tr_read<v_rd_off(1, 1, 0)>(vb), d1 = tr_read<v_rd_off(1, 1, 1)>(vb);
;   const s16x4 c2 = tr_read<v_rd_off(1, 2, 0)>(vb), d2 = tr_read<v_rd_off(1, 2, 1)>(vb), c3 = tr_read<v_rd_off(1, 3, 0)>(vb), d3 = tr_read<v_rd_off(1, 3, 1)>(vb);
;   asm volatile("s_waitcnt lgkmcnt(0)" ::: "memory"); SBAR();
;     ...
;   o[0] = __builtin_amdgcn_mfma_f32_32x32x16_bf16(pa0, PK(a0, b0), o[0], 0, 0, 0); o[1] = __builtin_amdgcn_mfma_f32_32x32x16_bf16(pa0, PK(c0, d0), o[1], 0, 0, 0);
.LBB0_531:
	v_pk_add_f32 v[222:223], v[66:67], v[222:223]
	v_pk_add_f32 v[224:225], v[68:69], v[224:225]
	v_pk_add_f32 v[226:227], v[70:71], v[226:227]
	v_pk_add_f32 v[228:229], v[72:73], v[228:229]
	v_pk_add_f32 v[230:231], v[74:75], v[230:231]
	v_pk_add_f32 v[232:233], v[76:77], v[232:233]
	v_pk_add_f32 v[234:235], v[78:79], v[234:235]
	v_pk_add_f32 v[236:237], v[80:81], v[236:237]
	v_pk_add_f32 v[222:223], v[222:223], v[224:225]
	v_pk_add_f32 v[226:227], v[226:227], v[228:229]
	v_pk_add_f32 v[230:231], v[230:231], v[232:233]
	v_pk_add_f32 v[234:235], v[234:235], v[236:237]
	v_pk_add_f32 v[222:223], v[222:223], v[226:227]
	v_pk_add_f32 v[230:231], v[230:231], v[234:235]
	v_pk_add_f32 v[222:223], v[222:223], v[230:231]
	v_add_f32_e32 v222, v222, v223
	v_add_f32_e32 v157, v157, v222
	v_add_u32_e32 v174, s5, v156
	ds_read_b64_tr_b16 v[66:67], v174 offset:0
	ds_read_b64_tr_b16 v[68:69], v174 offset:0x800
	ds_read_b64_tr_b16 v[158:159], v174 offset:0x200
	ds_read_b64_tr_b16 v[160:161], v174 offset:0xa00
	s_waitcnt lgkmcnt(4)
	s_barrier
	s_setprio 2
	ds_read_b64_tr_b16 v[70:71], v174 offset:0x1000
	ds_read_b64_tr_b16 v[72:73], v174 offset:0x1800
	ds_read_b64_tr_b16 v[162:163], v174 offset:0x1200
	ds_read_b64_tr_b16 v[164:165], v174 offset:0x1a00
	ds_read_b64_tr_b16 v[74:75], v174 offset:0x2000
	ds_read_b64_tr_b16 v[76:77], v174 offset:0x2800
	ds_read_b64_tr_b16 v[166:167], v174 offset:0x2200
	ds_read_b64_tr_b16 v[168:169], v174 offset:0x2a00
	ds_read_b64_tr_b16 v[78:79], v174 offset:0x3000
	ds_read_b64_tr_b16 v[80:81], v174 offset:0x3800
	ds_read_b64_tr_b16 v[170:171], v174 offset:0x3200
	ds_read_b64_tr_b16 v[172:173], v174 offset:0x3a00
	s_waitcnt lgkmcnt(14)
	v_mfma_f32_32x32x16_bf16 v[34:49], v[54:57], v[66:69], v[34:49]
	s_waitcnt lgkmcnt(12)
	v_mfma_f32_32x32x16_bf16 v[18:33], v[54:57], v[158:161], v[18:33]
	v_add_u32_e32 v55, s10, v239
	s_waitcnt lgkmcnt(10)
	v_mfma_f32_32x32x16_bf16 v[34:49], v[50:53], v[70:73], v[34:49]
	s_waitcnt lgkmcnt(8)
	v_mfma_f32_32x32x16_bf16 v[18:33], v[50:53], v[162:165], v[18:33]
	ds_read_b128 v[50:53], v55 offset:49152
	ds_read_b128 v[158:161], v55 offset:57344
	v_add_u32_e32 v55, s10, v250
	s_waitcnt lgkmcnt(8)
	v_mfma_f32_32x32x16_bf16 v[34:49], v[58:61], v[74:77], v[34:49]
	s_waitcnt lgkmcnt(6)
	v_mfma_f32_32x32x16_bf16 v[18:33], v[58:61], v[166:169], v[18:33]
	ds_read_b128 v[162:165], v55 offset:49152
	ds_read_b128 v[166:169], v55 offset:57344
	v_add_u32_e32 v55, s10, v251
	s_waitcnt lgkmcnt(6)
	v_mfma_f32_32x32x16_bf16 v[34:49], v[62:65], v[78:81], v[34:49]
	s_waitcnt lgkmcnt(4)
	v_mfma_f32_32x32x16_bf16 v[18:33], v[62:65], v[170:173], v[18:33]
	ds_read_b128 v[170:173], v55 offset:49152
	ds_read_b128 v[178:181], v55 offset:57344
	v_add_u32_e32 v55, s10, v252
	ds_read_b128 v[182:185], v55 offset:49152
	ds_read_b128 v[186:189], v55 offset:57344
	v_add_u32_e32 v55, s10, v253
	v_add_u32_e32 v54, s10, v175
	ds_read_b128 v[190:193], v55 offset:49152
	ds_read_b128 v[194:197], v55 offset:57344
	ds_read_b128 v[198:201], v54 offset:49152
	ds_read_b128 v[202:205], v54 offset:57344
	s_waitcnt lgkmcnt(11)
	v_mfma_f32_32x32x16_bf16 v[66:81], v[50:53], v[82:85], v[2:17]
	s_waitcnt lgkmcnt(9)
	v_mfma_f32_32x32x16_bf16 v[66:81], v[162:165], v[86:89], v[66:81]
	s_waitcnt lgkmcnt(7)
	v_mfma_f32_32x32x16_bf16 v[66:81], v[170:173], v[90:93], v[66:81]
	s_waitcnt lgkmcnt(5)
	v_mfma_f32_32x32x16_bf16 v[66:81], v[182:185], v[94:97], v[66:81]
	s_waitcnt lgkmcnt(3)
	v_mfma_f32_32x32x16_bf16 v[66:81], v[190:193], v[98:101], v[66:81]
	s_waitcnt lgkmcnt(1)
	v_mfma_f32_32x32x16_bf16 v[66:81], v[198:201], v[102:105], v[66:81]
	s_waitcnt lgkmcnt(0)
	v_mfma_f32_32x32x16_bf16 v[50:65], v[158:161], v[82:85], v[2:17]
	v_mfma_f32_32x32x16_bf16 v[50:65], v[166:169], v[86:89], v[50:65]
	v_mfma_f32_32x32x16_bf16 v[50:65], v[178:181], v[90:93], v[50:65]
	v_mfma_f32_32x32x16_bf16 v[50:65], v[186:189], v[94:97], v[50:65]
	v_mfma_f32_32x32x16_bf16 v[50:65], v[194:197], v[98:101], v[50:65]
	v_mfma_f32_32x32x16_bf16 v[50:65], v[202:205], v[102:105], v[50:65]
	s_setprio 0
	v_max3_f32 v158, v66, v67, v68
	v_max3_f32 v159, v69, v70, v71
	v_max3_f32 v158, v158, v72, v73
	v_max3_f32 v159, v159, v74, v75
	v_max3_f32 v158, v158, v76, v77
	v_max3_f32 v159, v159, v78, v79
	v_max3_f32 v158, v158, v80, v81
	s_nop 3
	v_max3_f32 v159, v159, v50, v51
	v_max3_f32 v158, v158, v52, v53
	v_max3_f32 v159, v159, v54, v55
	v_max3_f32 v158, v158, v56, v57
	v_max3_f32 v159, v159, v58, v59
	v_max3_f32 v158, v158, v60, v61
	v_max3_f32 v159, v159, v62, v63
	v_max3_f32 v158, v158, v64, v65
	v_max_f32_e32 v159, v158, v159
	v_cmp_ge_f32_e32 vcc, s93, v159
	s_cmp_eq_u64 vcc, exec
	s_barrier
	s_cbranch_scc0 .LBB0_541
